# halfround v2: half units run a specialised K-loop copy (no branches in the full loop; no A-half-1 DMA/ds_read, vmcnt(6))
# speedup vs baseline: 1.0184x; 1.0184x over previous
.LBB0_245:
	s_add_u32 s6, s90, 0x80
	s_addc_u32 s7, s91, 0
	s_add_u32 s8, s42, 0x100
	v_mov_b32_e32 v0, 0
	s_addc_u32 s66, s43, 0
	s_mov_b32 s42, 0
	v_mov_b32_e32 v1, v0
	v_mov_b64_e32 v[2:3], v[0:1]
	v_mov_b64_e32 v[4:5], v[0:1]
	v_mov_b64_e32 v[6:7], v[0:1]
	v_mov_b64_e32 v[8:9], v[0:1]
	v_mov_b64_e32 v[10:11], v[0:1]
	v_mov_b64_e32 v[12:13], v[0:1]
	v_mov_b64_e32 v[14:15], v[0:1]
	v_mov_b64_e32 v[16:17], v[0:1]
	v_mov_b64_e32 v[18:19], v[0:1]
	v_mov_b64_e32 v[20:21], v[0:1]
	v_mov_b64_e32 v[22:23], v[0:1]
	v_mov_b64_e32 v[24:25], v[0:1]
	v_mov_b64_e32 v[26:27], v[0:1]
	v_mov_b64_e32 v[28:29], v[0:1]
	v_mov_b64_e32 v[30:31], v[0:1]
	v_mov_b64_e32 v[32:33], v[0:1]
	v_mov_b64_e32 v[34:35], v[0:1]
	v_mov_b64_e32 v[36:37], v[0:1]
	v_mov_b64_e32 v[38:39], v[0:1]
	v_mov_b64_e32 v[40:41], v[0:1]
	v_mov_b64_e32 v[42:43], v[0:1]
	v_mov_b64_e32 v[44:45], v[0:1]
	v_mov_b64_e32 v[46:47], v[0:1]
	v_mov_b64_e32 v[48:49], v[0:1]
	v_mov_b64_e32 v[50:51], v[0:1]
	v_mov_b64_e32 v[52:53], v[0:1]
	v_mov_b64_e32 v[54:55], v[0:1]
	v_mov_b64_e32 v[56:57], v[0:1]
	v_mov_b64_e32 v[58:59], v[0:1]
	v_mov_b64_e32 v[60:61], v[0:1]
	v_mov_b64_e32 v[62:63], v[0:1]
	v_mov_b64_e32 v[64:65], v[0:1]
	v_mov_b64_e32 v[66:67], v[0:1]
	v_mov_b64_e32 v[68:69], v[0:1]
	v_mov_b64_e32 v[70:71], v[0:1]
	v_mov_b64_e32 v[72:73], v[0:1]
	v_mov_b64_e32 v[74:75], v[0:1]
	v_mov_b64_e32 v[76:77], v[0:1]
	v_mov_b64_e32 v[78:79], v[0:1]
	v_mov_b64_e32 v[80:81], v[0:1]
	v_mov_b64_e32 v[82:83], v[0:1]
	v_mov_b64_e32 v[84:85], v[0:1]
	v_mov_b64_e32 v[86:87], v[0:1]
	v_mov_b64_e32 v[88:89], v[0:1]
	v_mov_b64_e32 v[90:91], v[0:1]
	v_mov_b64_e32 v[92:93], v[0:1]
	v_mov_b64_e32 v[94:95], v[0:1]
	v_mov_b64_e32 v[96:97], v[0:1]
	v_mov_b64_e32 v[98:99], v[0:1]
	v_mov_b64_e32 v[100:101], v[0:1]
	v_mov_b64_e32 v[102:103], v[0:1]
	v_mov_b64_e32 v[104:105], v[0:1]
	v_mov_b64_e32 v[106:107], v[0:1]
	v_mov_b64_e32 v[108:109], v[0:1]
	v_mov_b64_e32 v[110:111], v[0:1]
	v_mov_b64_e32 v[112:113], v[0:1]
	v_mov_b64_e32 v[114:115], v[0:1]
	v_mov_b64_e32 v[116:117], v[0:1]
	v_mov_b64_e32 v[118:119], v[0:1]
	v_mov_b64_e32 v[120:121], v[0:1]
	v_mov_b64_e32 v[122:123], v[0:1]
	v_mov_b64_e32 v[124:125], v[0:1]
	v_mov_b64_e32 v[126:127], v[0:1]
	s_waitcnt lgkmcnt(0)
	v_add_u32_e32 v222, 0x10000, v157
	s_cmp_lg_u32 s98, 0
	s_cbranch_scc0 .LBB0_246
.Lhk_loop:
	s_add_i32 s90, s42, 2
	s_add_u32 s91, s6, 0x80
	s_addc_u32 s43, s7, 0
	s_cmp_eq_u32 s72, s42
	s_cselect_b32 s43, s89, s43
	s_cselect_b32 s42, s88, s91
	s_cselect_b32 s93, s1, s66
	s_cselect_b32 s92, s0, s8
	ds_read_b128 v[128:131], v222
	ds_read_b128 v[132:135], v222 offset:1024
	ds_read_b128 v[136:139], v222 offset:2048
	ds_read_b128 v[140:143], v222 offset:3072
	ds_read_b128 v[168:171], v222 offset:16384
	ds_read_b128 v[172:175], v222 offset:17408
	ds_read_b128 v[176:179], v222 offset:18432
	ds_read_b128 v[180:183], v222 offset:19456
	ds_read_b128 v[190:193], v188
	ds_read_b128 v[194:197], v188 offset:1024
	ds_read_b128 v[198:201], v188 offset:2048
	ds_read_b128 v[202:205], v188 offset:3072
	ds_read_b128 v[206:209], v188 offset:4096
	ds_read_b128 v[210:213], v188 offset:5120
	ds_read_b128 v[214:217], v188 offset:6144
	ds_read_b128 v[218:221], v188 offset:7168
	s_waitcnt vmcnt(6)
	s_waitcnt lgkmcnt(0)
	s_barrier
	s_setprio 1
	s_waitcnt lgkmcnt(0)
	v_mfma_f32_16x16x32_bf16 v[124:127], v[128:131], v[190:193], v[124:127]
	v_mfma_f32_16x16x32_bf16 v[120:123], v[136:139], v[190:193], v[120:123]
	v_mfma_f32_16x16x32_bf16 v[116:119], v[128:131], v[198:201], v[116:119]
	v_mfma_f32_16x16x32_bf16 v[112:115], v[136:139], v[198:201], v[112:115]
	v_mfma_f32_16x16x32_bf16 v[100:103], v[128:131], v[206:209], v[100:103]
	v_mfma_f32_16x16x32_bf16 v[96:99], v[136:139], v[206:209], v[96:99]
	v_mfma_f32_16x16x32_bf16 v[84:87], v[128:131], v[214:217], v[84:87]
	v_mfma_f32_16x16x32_bf16 v[80:83], v[136:139], v[214:217], v[80:83]
	v_mfma_f32_16x16x32_bf16 v[124:127], v[132:135], v[194:197], v[124:127]
	v_mfma_f32_16x16x32_bf16 v[120:123], v[140:143], v[194:197], v[120:123]
	v_mfma_f32_16x16x32_bf16 v[116:119], v[132:135], v[202:205], v[116:119]
	v_mfma_f32_16x16x32_bf16 v[112:115], v[140:143], v[202:205], v[112:115]
	v_mfma_f32_16x16x32_bf16 v[100:103], v[132:135], v[210:213], v[100:103]
	v_mfma_f32_16x16x32_bf16 v[96:99], v[140:143], v[210:213], v[96:99]
	v_mfma_f32_16x16x32_bf16 v[84:87], v[132:135], v[218:221], v[84:87]
	v_mfma_f32_16x16x32_bf16 v[80:83], v[140:143], v[218:221], v[80:83]
	s_setprio 0
	s_setprio 1
	v_mfma_f32_16x16x32_bf16 v[108:111], v[168:171], v[190:193], v[108:111]
	v_mfma_f32_16x16x32_bf16 v[104:107], v[176:179], v[190:193], v[104:107]
	v_mfma_f32_16x16x32_bf16 v[92:95], v[168:171], v[198:201], v[92:95]
	v_mfma_f32_16x16x32_bf16 v[88:91], v[176:179], v[198:201], v[88:91]
	v_mfma_f32_16x16x32_bf16 v[76:79], v[168:171], v[206:209], v[76:79]
	v_mfma_f32_16x16x32_bf16 v[72:75], v[176:179], v[206:209], v[72:75]
	v_mfma_f32_16x16x32_bf16 v[68:71], v[168:171], v[214:217], v[68:71]
	v_mfma_f32_16x16x32_bf16 v[64:67], v[176:179], v[214:217], v[64:67]
	v_mfma_f32_16x16x32_bf16 v[108:111], v[172:175], v[194:197], v[108:111]
	v_mfma_f32_16x16x32_bf16 v[104:107], v[180:183], v[194:197], v[104:107]
	v_mfma_f32_16x16x32_bf16 v[92:95], v[172:175], v[202:205], v[92:95]
	v_mfma_f32_16x16x32_bf16 v[88:91], v[180:183], v[202:205], v[88:91]
	v_mfma_f32_16x16x32_bf16 v[76:79], v[172:175], v[210:213], v[76:79]
	v_mfma_f32_16x16x32_bf16 v[72:75], v[180:183], v[210:213], v[72:75]
	v_mfma_f32_16x16x32_bf16 v[68:71], v[172:175], v[218:221], v[68:71]
	v_mfma_f32_16x16x32_bf16 v[64:67], v[180:183], v[218:221], v[64:67]
	s_setprio 0
	s_barrier
	s_add_i32 m0, s15, 0x10000
	s_nop 0
	global_load_lds_dwordx4 v148, s[92:93]
	s_add_i32 m0, s15, 0x12000
	s_nop 0
	global_load_lds_dwordx4 v152, s[92:93]
	s_add_i32 m0, s15, 0x14000
	s_add_u32 s92, s92, s21
	s_addc_u32 s93, s93, 0
	global_load_lds_dwordx4 v148, s[92:93]
	s_add_i32 m0, s15, 0x16000
	s_nop 0
	global_load_lds_dwordx4 v152, s[92:93]
	s_mov_b32 m0, s68
	s_nop 0
	global_load_lds_dwordx4 v146, s[42:43]
	s_mov_b32 m0, s23
	s_nop 0
	global_load_lds_dwordx4 v150, s[42:43]
	s_waitcnt vmcnt(6)
	s_waitcnt lgkmcnt(0)
	s_barrier
	s_barrier
	ds_read_b128 v[128:131], v222 offset:32768
	ds_read_b128 v[132:135], v222 offset:33792
	ds_read_b128 v[136:139], v222 offset:34816
	ds_read_b128 v[140:143], v222 offset:35840
	ds_read_b128 v[168:171], v222 offset:49152
	ds_read_b128 v[172:175], v222 offset:50176
	ds_read_b128 v[176:179], v222 offset:51200
	ds_read_b128 v[180:183], v222 offset:52224
	s_add_u32 s42, s42, s48
	s_addc_u32 s43, s43, 0
	ds_read_b128 v[190:193], v188 offset:32768
	ds_read_b128 v[194:197], v188 offset:33792
	ds_read_b128 v[198:201], v188 offset:34816
	ds_read_b128 v[202:205], v188 offset:35840
	ds_read_b128 v[206:209], v188 offset:36864
	ds_read_b128 v[210:213], v188 offset:37888
	ds_read_b128 v[214:217], v188 offset:38912
	ds_read_b128 v[218:221], v188 offset:39936
	s_waitcnt vmcnt(6)
	s_waitcnt lgkmcnt(0)
	s_barrier
	s_setprio 1
	s_waitcnt lgkmcnt(0)
	v_mfma_f32_16x16x32_bf16 v[124:127], v[128:131], v[190:193], v[124:127]
	v_mfma_f32_16x16x32_bf16 v[120:123], v[136:139], v[190:193], v[120:123]
	v_mfma_f32_16x16x32_bf16 v[116:119], v[128:131], v[198:201], v[116:119]
	v_mfma_f32_16x16x32_bf16 v[112:115], v[136:139], v[198:201], v[112:115]
	v_mfma_f32_16x16x32_bf16 v[100:103], v[128:131], v[206:209], v[100:103]
	v_mfma_f32_16x16x32_bf16 v[96:99], v[136:139], v[206:209], v[96:99]
	v_mfma_f32_16x16x32_bf16 v[84:87], v[128:131], v[214:217], v[84:87]
	v_mfma_f32_16x16x32_bf16 v[80:83], v[136:139], v[214:217], v[80:83]
	v_mfma_f32_16x16x32_bf16 v[124:127], v[132:135], v[194:197], v[124:127]
	v_mfma_f32_16x16x32_bf16 v[120:123], v[140:143], v[194:197], v[120:123]
	v_mfma_f32_16x16x32_bf16 v[116:119], v[132:135], v[202:205], v[116:119]
	v_mfma_f32_16x16x32_bf16 v[112:115], v[140:143], v[202:205], v[112:115]
	v_mfma_f32_16x16x32_bf16 v[100:103], v[132:135], v[210:213], v[100:103]
	v_mfma_f32_16x16x32_bf16 v[96:99], v[140:143], v[210:213], v[96:99]
	v_mfma_f32_16x16x32_bf16 v[84:87], v[132:135], v[218:221], v[84:87]
	v_mfma_f32_16x16x32_bf16 v[80:83], v[140:143], v[218:221], v[80:83]
	s_setprio 0
	s_setprio 1
	v_mfma_f32_16x16x32_bf16 v[108:111], v[168:171], v[190:193], v[108:111]
	v_mfma_f32_16x16x32_bf16 v[104:107], v[176:179], v[190:193], v[104:107]
	v_mfma_f32_16x16x32_bf16 v[92:95], v[168:171], v[198:201], v[92:95]
	v_mfma_f32_16x16x32_bf16 v[88:91], v[176:179], v[198:201], v[88:91]
	v_mfma_f32_16x16x32_bf16 v[76:79], v[168:171], v[206:209], v[76:79]
	v_mfma_f32_16x16x32_bf16 v[72:75], v[176:179], v[206:209], v[72:75]
	v_mfma_f32_16x16x32_bf16 v[68:71], v[168:171], v[214:217], v[68:71]
	v_mfma_f32_16x16x32_bf16 v[64:67], v[176:179], v[214:217], v[64:67]
	v_mfma_f32_16x16x32_bf16 v[108:111], v[172:175], v[194:197], v[108:111]
	v_mfma_f32_16x16x32_bf16 v[104:107], v[180:183], v[194:197], v[104:107]
	v_mfma_f32_16x16x32_bf16 v[92:95], v[172:175], v[202:205], v[92:95]
	v_mfma_f32_16x16x32_bf16 v[88:91], v[180:183], v[202:205], v[88:91]
	v_mfma_f32_16x16x32_bf16 v[76:79], v[172:175], v[210:213], v[76:79]
	v_mfma_f32_16x16x32_bf16 v[72:75], v[180:183], v[210:213], v[72:75]
	v_mfma_f32_16x16x32_bf16 v[68:71], v[172:175], v[218:221], v[68:71]
	v_mfma_f32_16x16x32_bf16 v[64:67], v[180:183], v[218:221], v[64:67]
	s_setprio 0
	s_barrier
	s_sub_u32 s92, s92, s21
	s_subb_u32 s93, s93, 0
	s_add_i32 m0, s15, 0x17f80
	s_nop 0
	global_load_lds_dwordx4 v148, s[92:93] offset:128
	s_add_i32 m0, s15, 0x19f80
	s_nop 0
	global_load_lds_dwordx4 v152, s[92:93] offset:128
	s_add_u32 s92, s92, s21
	s_addc_u32 s93, s93, 0
	s_add_i32 m0, s15, 0x1bf80
	s_add_u32 s6, s6, 0x100
	s_addc_u32 s7, s7, 0
	global_load_lds_dwordx4 v148, s[92:93] offset:128
	s_add_i32 m0, s15, 0x1df80
	s_sub_u32 s42, s42, s48
	s_subb_u32 s43, s43, 0
	global_load_lds_dwordx4 v152, s[92:93] offset:128
	s_add_i32 m0, s64, 0xffffff80
	s_add_u32 s8, s8, 0x100
	s_addc_u32 s66, s66, 0
	global_load_lds_dwordx4 v146, s[42:43] offset:128
	s_add_i32 m0, s65, 0xffffff80
	s_nop 0
	global_load_lds_dwordx4 v150, s[42:43] offset:128
	s_waitcnt vmcnt(6)
	s_waitcnt lgkmcnt(0)
	s_barrier
	s_barrier
	s_cmp_ge_u32 s90, s55
	s_mov_b32 s42, s90
	s_cbranch_scc0 .Lhk_loop
	s_branch .Lhk_exit
.LBB0_246:
	s_add_i32 s90, s42, 2
	s_add_u32 s91, s6, 0x80
	s_addc_u32 s43, s7, 0
	s_cmp_eq_u32 s72, s42
	s_cselect_b32 s43, s89, s43
	s_cselect_b32 s42, s88, s91
	s_cselect_b32 s93, s1, s66
	s_cselect_b32 s92, s0, s8
	ds_read_b128 v[128:131], v222
	ds_read_b128 v[132:135], v222 offset:1024
	ds_read_b128 v[136:139], v222 offset:2048
	ds_read_b128 v[140:143], v222 offset:3072
	ds_read_b128 v[168:171], v222 offset:16384
	ds_read_b128 v[172:175], v222 offset:17408
	ds_read_b128 v[176:179], v222 offset:18432
	ds_read_b128 v[180:183], v222 offset:19456
	s_add_i32 m0, s68, 0xc000
	ds_read_b128 v[190:193], v188
	ds_read_b128 v[194:197], v188 offset:1024
	ds_read_b128 v[198:201], v188 offset:2048
	ds_read_b128 v[202:205], v188 offset:3072
	ds_read_b128 v[206:209], v188 offset:4096
	ds_read_b128 v[210:213], v188 offset:5120
	ds_read_b128 v[214:217], v188 offset:6144
	ds_read_b128 v[218:221], v188 offset:7168
	global_load_lds_dwordx4 v162, s[6:7]
	s_add_i32 m0, s68, 0xe000
	s_nop 0
	global_load_lds_dwordx4 v164, s[6:7]
	s_waitcnt vmcnt(8)
	s_waitcnt lgkmcnt(0)
	s_barrier
	s_setprio 1
	s_waitcnt lgkmcnt(0)
	v_mfma_f32_16x16x32_bf16 v[124:127], v[128:131], v[190:193], v[124:127]
	v_mfma_f32_16x16x32_bf16 v[120:123], v[136:139], v[190:193], v[120:123]
	v_mfma_f32_16x16x32_bf16 v[116:119], v[128:131], v[198:201], v[116:119]
	v_mfma_f32_16x16x32_bf16 v[112:115], v[136:139], v[198:201], v[112:115]
	v_mfma_f32_16x16x32_bf16 v[100:103], v[128:131], v[206:209], v[100:103]
	v_mfma_f32_16x16x32_bf16 v[96:99], v[136:139], v[206:209], v[96:99]
	v_mfma_f32_16x16x32_bf16 v[84:87], v[128:131], v[214:217], v[84:87]
	v_mfma_f32_16x16x32_bf16 v[80:83], v[136:139], v[214:217], v[80:83]
	v_mfma_f32_16x16x32_bf16 v[124:127], v[132:135], v[194:197], v[124:127]
	v_mfma_f32_16x16x32_bf16 v[120:123], v[140:143], v[194:197], v[120:123]
	v_mfma_f32_16x16x32_bf16 v[116:119], v[132:135], v[202:205], v[116:119]
	v_mfma_f32_16x16x32_bf16 v[112:115], v[140:143], v[202:205], v[112:115]
	v_mfma_f32_16x16x32_bf16 v[100:103], v[132:135], v[210:213], v[100:103]
	v_mfma_f32_16x16x32_bf16 v[96:99], v[140:143], v[210:213], v[96:99]
	v_mfma_f32_16x16x32_bf16 v[84:87], v[132:135], v[218:221], v[84:87]
	v_mfma_f32_16x16x32_bf16 v[80:83], v[140:143], v[218:221], v[80:83]
	s_setprio 0
	s_setprio 1
	v_mfma_f32_16x16x32_bf16 v[108:111], v[168:171], v[190:193], v[108:111]
	v_mfma_f32_16x16x32_bf16 v[104:107], v[176:179], v[190:193], v[104:107]
	v_mfma_f32_16x16x32_bf16 v[92:95], v[168:171], v[198:201], v[92:95]
	v_mfma_f32_16x16x32_bf16 v[88:91], v[176:179], v[198:201], v[88:91]
	v_mfma_f32_16x16x32_bf16 v[76:79], v[168:171], v[206:209], v[76:79]
	v_mfma_f32_16x16x32_bf16 v[72:75], v[176:179], v[206:209], v[72:75]
	v_mfma_f32_16x16x32_bf16 v[68:71], v[168:171], v[214:217], v[68:71]
	v_mfma_f32_16x16x32_bf16 v[64:67], v[176:179], v[214:217], v[64:67]
	v_mfma_f32_16x16x32_bf16 v[108:111], v[172:175], v[194:197], v[108:111]
	v_mfma_f32_16x16x32_bf16 v[104:107], v[180:183], v[194:197], v[104:107]
	v_mfma_f32_16x16x32_bf16 v[92:95], v[172:175], v[202:205], v[92:95]
	v_mfma_f32_16x16x32_bf16 v[88:91], v[180:183], v[202:205], v[88:91]
	v_mfma_f32_16x16x32_bf16 v[76:79], v[172:175], v[210:213], v[76:79]
	v_mfma_f32_16x16x32_bf16 v[72:75], v[180:183], v[210:213], v[72:75]
	v_mfma_f32_16x16x32_bf16 v[68:71], v[172:175], v[218:221], v[68:71]
	v_mfma_f32_16x16x32_bf16 v[64:67], v[180:183], v[218:221], v[64:67]
	s_setprio 0
	s_barrier
	s_add_i32 m0, s15, 0x10000
	ds_read_b128 v[190:193], v188 offset:16384
	ds_read_b128 v[194:197], v188 offset:17408
	ds_read_b128 v[198:201], v188 offset:18432
	ds_read_b128 v[202:205], v188 offset:19456
	ds_read_b128 v[206:209], v188 offset:20480
	ds_read_b128 v[210:213], v188 offset:21504
	ds_read_b128 v[214:217], v188 offset:22528
	ds_read_b128 v[218:221], v188 offset:23552
	global_load_lds_dwordx4 v148, s[92:93]
	s_add_i32 m0, s15, 0x12000
	s_nop 0
	global_load_lds_dwordx4 v152, s[92:93]
	s_add_i32 m0, s15, 0x14000
	s_add_u32 s92, s92, s21
	s_addc_u32 s93, s93, 0
	global_load_lds_dwordx4 v148, s[92:93]
	s_add_i32 m0, s15, 0x16000
	s_nop 0
	global_load_lds_dwordx4 v152, s[92:93]
	s_mov_b32 m0, s68
	s_nop 0
	global_load_lds_dwordx4 v146, s[42:43]
	s_mov_b32 m0, s23
	s_nop 0
	global_load_lds_dwordx4 v150, s[42:43]
	s_waitcnt vmcnt(8)
	s_waitcnt lgkmcnt(0)
	s_barrier
	s_setprio 1
	s_waitcnt lgkmcnt(0)
	v_mfma_f32_16x16x32_bf16 v[60:63], v[128:131], v[190:193], v[60:63]
	v_mfma_f32_16x16x32_bf16 v[56:59], v[136:139], v[190:193], v[56:59]
	v_mfma_f32_16x16x32_bf16 v[52:55], v[128:131], v[198:201], v[52:55]
	v_mfma_f32_16x16x32_bf16 v[48:51], v[136:139], v[198:201], v[48:51]
	v_mfma_f32_16x16x32_bf16 v[36:39], v[128:131], v[206:209], v[36:39]
	v_mfma_f32_16x16x32_bf16 v[32:35], v[136:139], v[206:209], v[32:35]
	v_mfma_f32_16x16x32_bf16 v[20:23], v[128:131], v[214:217], v[20:23]
	v_mfma_f32_16x16x32_bf16 v[16:19], v[136:139], v[214:217], v[16:19]
	v_mfma_f32_16x16x32_bf16 v[60:63], v[132:135], v[194:197], v[60:63]
	v_mfma_f32_16x16x32_bf16 v[56:59], v[140:143], v[194:197], v[56:59]
	v_mfma_f32_16x16x32_bf16 v[52:55], v[132:135], v[202:205], v[52:55]
	v_mfma_f32_16x16x32_bf16 v[48:51], v[140:143], v[202:205], v[48:51]
	v_mfma_f32_16x16x32_bf16 v[36:39], v[132:135], v[210:213], v[36:39]
	v_mfma_f32_16x16x32_bf16 v[32:35], v[140:143], v[210:213], v[32:35]
	v_mfma_f32_16x16x32_bf16 v[20:23], v[132:135], v[218:221], v[20:23]
	v_mfma_f32_16x16x32_bf16 v[16:19], v[140:143], v[218:221], v[16:19]
	s_setprio 0
	s_setprio 1
	v_mfma_f32_16x16x32_bf16 v[44:47], v[168:171], v[190:193], v[44:47]
	v_mfma_f32_16x16x32_bf16 v[40:43], v[176:179], v[190:193], v[40:43]
	v_mfma_f32_16x16x32_bf16 v[28:31], v[168:171], v[198:201], v[28:31]
	v_mfma_f32_16x16x32_bf16 v[24:27], v[176:179], v[198:201], v[24:27]
	v_mfma_f32_16x16x32_bf16 v[12:15], v[168:171], v[206:209], v[12:15]
	v_mfma_f32_16x16x32_bf16 v[8:11], v[176:179], v[206:209], v[8:11]
	v_mfma_f32_16x16x32_bf16 v[4:7], v[168:171], v[214:217], v[4:7]
	v_mfma_f32_16x16x32_bf16 v[0:3], v[176:179], v[214:217], v[0:3]
	v_mfma_f32_16x16x32_bf16 v[44:47], v[172:175], v[194:197], v[44:47]
	v_mfma_f32_16x16x32_bf16 v[40:43], v[180:183], v[194:197], v[40:43]
	v_mfma_f32_16x16x32_bf16 v[28:31], v[172:175], v[202:205], v[28:31]
	v_mfma_f32_16x16x32_bf16 v[24:27], v[180:183], v[202:205], v[24:27]
	v_mfma_f32_16x16x32_bf16 v[12:15], v[172:175], v[210:213], v[12:15]
	v_mfma_f32_16x16x32_bf16 v[8:11], v[180:183], v[210:213], v[8:11]
	v_mfma_f32_16x16x32_bf16 v[4:7], v[172:175], v[218:221], v[4:7]
	v_mfma_f32_16x16x32_bf16 v[0:3], v[180:183], v[218:221], v[0:3]
	s_setprio 0
	s_barrier
	ds_read_b128 v[128:131], v222 offset:32768
	ds_read_b128 v[132:135], v222 offset:33792
	ds_read_b128 v[136:139], v222 offset:34816
	ds_read_b128 v[140:143], v222 offset:35840
	ds_read_b128 v[168:171], v222 offset:49152
	ds_read_b128 v[172:175], v222 offset:50176
	ds_read_b128 v[176:179], v222 offset:51200
	ds_read_b128 v[180:183], v222 offset:52224
	s_add_u32 s42, s42, s48
	s_addc_u32 s43, s43, 0
	s_mov_b32 m0, s40
	ds_read_b128 v[190:193], v188 offset:32768
	ds_read_b128 v[194:197], v188 offset:33792
	ds_read_b128 v[198:201], v188 offset:34816
	ds_read_b128 v[202:205], v188 offset:35840
	ds_read_b128 v[206:209], v188 offset:36864
	ds_read_b128 v[210:213], v188 offset:37888
	ds_read_b128 v[214:217], v188 offset:38912
	ds_read_b128 v[218:221], v188 offset:39936
	global_load_lds_dwordx4 v146, s[42:43]
	s_mov_b32 m0, s41
	s_nop 0
	global_load_lds_dwordx4 v150, s[42:43]
	s_waitcnt vmcnt(8)
	s_waitcnt lgkmcnt(0)
	s_barrier
	s_setprio 1
	s_waitcnt lgkmcnt(0)
	v_mfma_f32_16x16x32_bf16 v[124:127], v[128:131], v[190:193], v[124:127]
	v_mfma_f32_16x16x32_bf16 v[120:123], v[136:139], v[190:193], v[120:123]
	v_mfma_f32_16x16x32_bf16 v[116:119], v[128:131], v[198:201], v[116:119]
	v_mfma_f32_16x16x32_bf16 v[112:115], v[136:139], v[198:201], v[112:115]
	v_mfma_f32_16x16x32_bf16 v[100:103], v[128:131], v[206:209], v[100:103]
	v_mfma_f32_16x16x32_bf16 v[96:99], v[136:139], v[206:209], v[96:99]
	v_mfma_f32_16x16x32_bf16 v[84:87], v[128:131], v[214:217], v[84:87]
	v_mfma_f32_16x16x32_bf16 v[80:83], v[136:139], v[214:217], v[80:83]
	v_mfma_f32_16x16x32_bf16 v[124:127], v[132:135], v[194:197], v[124:127]
	v_mfma_f32_16x16x32_bf16 v[120:123], v[140:143], v[194:197], v[120:123]
	v_mfma_f32_16x16x32_bf16 v[116:119], v[132:135], v[202:205], v[116:119]
	v_mfma_f32_16x16x32_bf16 v[112:115], v[140:143], v[202:205], v[112:115]
	v_mfma_f32_16x16x32_bf16 v[100:103], v[132:135], v[210:213], v[100:103]
	v_mfma_f32_16x16x32_bf16 v[96:99], v[140:143], v[210:213], v[96:99]
	v_mfma_f32_16x16x32_bf16 v[84:87], v[132:135], v[218:221], v[84:87]
	v_mfma_f32_16x16x32_bf16 v[80:83], v[140:143], v[218:221], v[80:83]
	s_setprio 0
	s_setprio 1
	v_mfma_f32_16x16x32_bf16 v[108:111], v[168:171], v[190:193], v[108:111]
	v_mfma_f32_16x16x32_bf16 v[104:107], v[176:179], v[190:193], v[104:107]
	v_mfma_f32_16x16x32_bf16 v[92:95], v[168:171], v[198:201], v[92:95]
	v_mfma_f32_16x16x32_bf16 v[88:91], v[176:179], v[198:201], v[88:91]
	v_mfma_f32_16x16x32_bf16 v[76:79], v[168:171], v[206:209], v[76:79]
	v_mfma_f32_16x16x32_bf16 v[72:75], v[176:179], v[206:209], v[72:75]
	v_mfma_f32_16x16x32_bf16 v[68:71], v[168:171], v[214:217], v[68:71]
	v_mfma_f32_16x16x32_bf16 v[64:67], v[176:179], v[214:217], v[64:67]
	v_mfma_f32_16x16x32_bf16 v[108:111], v[172:175], v[194:197], v[108:111]
	v_mfma_f32_16x16x32_bf16 v[104:107], v[180:183], v[194:197], v[104:107]
	v_mfma_f32_16x16x32_bf16 v[92:95], v[172:175], v[202:205], v[92:95]
	v_mfma_f32_16x16x32_bf16 v[88:91], v[180:183], v[202:205], v[88:91]
	v_mfma_f32_16x16x32_bf16 v[76:79], v[172:175], v[210:213], v[76:79]
	v_mfma_f32_16x16x32_bf16 v[72:75], v[180:183], v[210:213], v[72:75]
	v_mfma_f32_16x16x32_bf16 v[68:71], v[172:175], v[218:221], v[68:71]
	v_mfma_f32_16x16x32_bf16 v[64:67], v[180:183], v[218:221], v[64:67]
	s_setprio 0
	s_barrier
	s_sub_u32 s92, s92, s21
	s_subb_u32 s93, s93, 0
	s_add_i32 m0, s15, 0x17f80
	ds_read_b128 v[190:193], v188 offset:49152
	ds_read_b128 v[194:197], v188 offset:50176
	ds_read_b128 v[198:201], v188 offset:51200
	ds_read_b128 v[202:205], v188 offset:52224
	ds_read_b128 v[206:209], v188 offset:53248
	ds_read_b128 v[210:213], v188 offset:54272
	ds_read_b128 v[214:217], v188 offset:55296
	ds_read_b128 v[218:221], v188 offset:56320
	global_load_lds_dwordx4 v148, s[92:93] offset:128
	s_add_i32 m0, s15, 0x19f80
	s_nop 0
	global_load_lds_dwordx4 v152, s[92:93] offset:128
	s_add_u32 s92, s92, s21
	s_addc_u32 s93, s93, 0
	s_add_i32 m0, s15, 0x1bf80
	s_add_u32 s6, s6, 0x100
	s_addc_u32 s7, s7, 0
	global_load_lds_dwordx4 v148, s[92:93] offset:128
	s_add_i32 m0, s15, 0x1df80
	s_sub_u32 s42, s42, s48
	s_subb_u32 s43, s43, 0
	global_load_lds_dwordx4 v152, s[92:93] offset:128
	s_add_i32 m0, s64, 0xffffff80
	s_add_u32 s8, s8, 0x100
	s_addc_u32 s66, s66, 0
	global_load_lds_dwordx4 v146, s[42:43] offset:128
	s_add_i32 m0, s65, 0xffffff80
	s_nop 0
	global_load_lds_dwordx4 v150, s[42:43] offset:128
	s_waitcnt vmcnt(8)
	s_waitcnt lgkmcnt(0)
	s_barrier
	s_setprio 1
	s_waitcnt lgkmcnt(0)
	v_mfma_f32_16x16x32_bf16 v[60:63], v[128:131], v[190:193], v[60:63]
	v_mfma_f32_16x16x32_bf16 v[56:59], v[136:139], v[190:193], v[56:59]
	v_mfma_f32_16x16x32_bf16 v[52:55], v[128:131], v[198:201], v[52:55]
	v_mfma_f32_16x16x32_bf16 v[48:51], v[136:139], v[198:201], v[48:51]
	v_mfma_f32_16x16x32_bf16 v[36:39], v[128:131], v[206:209], v[36:39]
	v_mfma_f32_16x16x32_bf16 v[32:35], v[136:139], v[206:209], v[32:35]
	v_mfma_f32_16x16x32_bf16 v[20:23], v[128:131], v[214:217], v[20:23]
	v_mfma_f32_16x16x32_bf16 v[16:19], v[136:139], v[214:217], v[16:19]
	v_mfma_f32_16x16x32_bf16 v[60:63], v[132:135], v[194:197], v[60:63]
	v_mfma_f32_16x16x32_bf16 v[56:59], v[140:143], v[194:197], v[56:59]
	v_mfma_f32_16x16x32_bf16 v[52:55], v[132:135], v[202:205], v[52:55]
	v_mfma_f32_16x16x32_bf16 v[48:51], v[140:143], v[202:205], v[48:51]
	v_mfma_f32_16x16x32_bf16 v[36:39], v[132:135], v[210:213], v[36:39]
	v_mfma_f32_16x16x32_bf16 v[32:35], v[140:143], v[210:213], v[32:35]
	v_mfma_f32_16x16x32_bf16 v[20:23], v[132:135], v[218:221], v[20:23]
	v_mfma_f32_16x16x32_bf16 v[16:19], v[140:143], v[218:221], v[16:19]
	s_setprio 0
	s_setprio 1
	v_mfma_f32_16x16x32_bf16 v[44:47], v[168:171], v[190:193], v[44:47]
	v_mfma_f32_16x16x32_bf16 v[40:43], v[176:179], v[190:193], v[40:43]
	v_mfma_f32_16x16x32_bf16 v[28:31], v[168:171], v[198:201], v[28:31]
	v_mfma_f32_16x16x32_bf16 v[24:27], v[176:179], v[198:201], v[24:27]
	v_mfma_f32_16x16x32_bf16 v[12:15], v[168:171], v[206:209], v[12:15]
	v_mfma_f32_16x16x32_bf16 v[8:11], v[176:179], v[206:209], v[8:11]
	v_mfma_f32_16x16x32_bf16 v[4:7], v[168:171], v[214:217], v[4:7]
	v_mfma_f32_16x16x32_bf16 v[0:3], v[176:179], v[214:217], v[0:3]
	v_mfma_f32_16x16x32_bf16 v[44:47], v[172:175], v[194:197], v[44:47]
	v_mfma_f32_16x16x32_bf16 v[40:43], v[180:183], v[194:197], v[40:43]
	v_mfma_f32_16x16x32_bf16 v[28:31], v[172:175], v[202:205], v[28:31]
	v_mfma_f32_16x16x32_bf16 v[24:27], v[180:183], v[202:205], v[24:27]
	v_mfma_f32_16x16x32_bf16 v[12:15], v[172:175], v[210:213], v[12:15]
	v_mfma_f32_16x16x32_bf16 v[8:11], v[180:183], v[210:213], v[8:11]
	v_mfma_f32_16x16x32_bf16 v[4:7], v[172:175], v[218:221], v[4:7]
	v_mfma_f32_16x16x32_bf16 v[0:3], v[180:183], v[218:221], v[0:3]
	s_setprio 0
	s_barrier
	s_cmp_ge_u32 s90, s55
	s_mov_b32 s42, s90
	s_cbranch_scc0 .LBB0_246
.Lhk_exit:
	s_and_b64 vcc, exec, s[86:87]
	s_cbranch_vccz .LBB0_249
	s_barrier
